# nt policy also on XN2 and final-norm row loads
# baseline (speedup 1.0000x reference)
; __device__ __forceinline__ unsigned pk2(float lo, float hi) { unsigned r; asm volatile("v_cvt_pk_bf16_f32 %0, %1, %2" : "=v"(r) : "v"(lo), "v"(hi)); return r; }
; __device__ __forceinline__ void xn_phase(const Params& p, int layer, int which, char* smem) {
;     ...
;     for (int row = blockIdx.x * 8 + wid; row < nrows; row += gridDim.x * 8) {
;         const bool isc = row >= SEQ; const float* src = isc ? csrc + (size_t)(row - SEQ) * DM : lsrc + (size_t)row * DM;
;         const float* sh = sv + (isc ? 4096 : 0); const float* sc = sh + 2048;
;         f32x4 v[8]; float ss = 0.f;
; #pragma unroll
;         for (int j = 0; j < 8; ++j) { v[j] = *(const f32x4*)(src + 4 * (lane + 64 * j)); ss += (v[j][0] * v[j][0] + v[j][1] * v[j][1]) + (v[j][2] * v[j][2] + v[j][3] * v[j][3]); }
;         const float rinv = rsqrtf(wave_sum(ss) * (1.f / DM) + 1e-6f);
; #pragma unroll
;         for (int j = 0; j < 8; ++j) { const int c = 4 * (lane + 64 * j); const f32x4 gg = *(const f32x4*)(g + c); float y[4];
; #pragma unroll
;             for (int e = 0; e < 4; ++e) y[e] = v[j][e] * rinv * gg[e] * (1.f + sc[c + e]) + sh[c + e];
;             u32x2 o; o.x = pk2(y[0], y[1]); o.y = pk2(y[2], y[3]); *(u32x2*)(XN + (size_t)row * DM + c) = o; }
.LBB0_1334:
	s_or_b64 exec, exec, s[14:15]
	v_mov_b32_e32 v51, v1
	v_lshl_add_u64 v[4:5], v[2:3], 0, v[50:51]
	global_load_dwordx4 v[30:33], v[4:5], off nt
	global_load_dwordx4 v[26:29], v[4:5], off offset:1024 nt
	global_load_dwordx4 v[22:25], v[4:5], off offset:2048 nt
	global_load_dwordx4 v[18:21], v[4:5], off offset:3072 nt
	v_mov_b32_e32 v53, v1
	v_lshl_add_u64 v[4:5], v[2:3], 0, v[52:53]
	global_load_dwordx4 v[14:17], v[4:5], off nt
	v_mov_b32_e32 v55, v1
	v_mov_b32_e32 v57, v1
	v_mov_b32_e32 v59, v1
	s_mov_b32 s0, 0x800000
	v_add_u32_e32 v0, s95, v0
	s_waitcnt vmcnt(4)
	v_mov_b32_e32 v8, v31
	s_waitcnt vmcnt(3)
	v_mov_b32_e32 v9, v27
	v_mov_b32_e32 v6, v30
	v_mov_b32_e32 v7, v26
	v_pk_mul_f32 v[8:9], v[8:9], v[8:9]
	v_mov_b32_e32 v10, v33
	v_mov_b32_e32 v11, v29
	v_pk_fma_f32 v[6:7], v[6:7], v[6:7], v[8:9]
	v_mov_b32_e32 v8, v32
	v_mov_b32_e32 v9, v28
	v_pk_mul_f32 v[10:11], v[10:11], v[10:11]
	s_nop 0
	v_pk_fma_f32 v[8:9], v[8:9], v[8:9], v[10:11]
	s_waitcnt vmcnt(2)
	v_pk_mul_f32 v[10:11], v[22:23], v[22:23]
	v_pk_add_f32 v[6:7], v[6:7], v[8:9]
	v_pk_mul_f32 v[8:9], v[24:25], v[24:25]
	v_pk_add_f32 v[4:5], v[6:7], v[6:7] op_sel:[0,1] op_sel_hi:[1,0]
	v_pk_mov_b32 v[12:13], v[10:11], v[8:9] op_sel:[1,0]
	v_mov_b32_e32 v11, v9
	v_pk_add_f32 v[8:9], v[12:13], v[10:11]
	s_waitcnt vmcnt(0)
	v_mul_f32_e32 v10, v14, v14
	v_mul_f32_e32 v11, v15, v15
	v_pk_add_f32 v[6:7], v[8:9], v[8:9] op_sel:[0,1] op_sel_hi:[1,0]
	v_mov_b32_e32 v5, v10
	v_mov_b32_e32 v7, v11
	v_pk_add_f32 v[4:5], v[4:5], v[6:7]
	v_mul_f32_e32 v6, v19, v19
	v_mul_f32_e32 v8, v21, v21
	v_mul_f32_e32 v12, v16, v16
	v_mul_f32_e32 v13, v17, v17
	v_pk_fma_f32 v[6:7], v[18:19], v[18:19], v[6:7] op_sel_hi:[1,1,0]
	v_pk_fma_f32 v[8:9], v[20:21], v[20:21], v[8:9] op_sel_hi:[1,1,0]
	v_mov_b32_e32 v7, v12
	v_mov_b32_e32 v9, v13
	v_pk_add_f32 v[6:7], v[6:7], v[8:9]
	s_nop 0
	v_pk_add_f32 v[36:37], v[4:5], v[6:7]
	v_lshl_add_u64 v[4:5], v[2:3], 0, v[54:55]
	global_load_dwordx4 v[10:13], v[4:5], off nt
	v_pk_add_f32 v[36:37], v[36:37], v[36:37] op_sel:[0,1] op_sel_hi:[1,0]
	s_waitcnt vmcnt(0)
	v_pk_mul_f32 v[4:5], v[12:13], v[12:13]
	v_pk_mul_f32 v[6:7], v[10:11], v[10:11]
	s_nop 0
	v_pk_mov_b32 v[8:9], v[6:7], v[4:5] op_sel:[1,0]
	v_mov_b32_e32 v7, v5
	v_lshl_add_u64 v[4:5], v[2:3], 0, v[56:57]
	v_lshl_add_u64 v[2:3], v[2:3], 0, v[58:59]
	v_pk_add_f32 v[60:61], v[8:9], v[6:7]
	global_load_dwordx4 v[6:9], v[4:5], off nt
	v_pk_add_f32 v[60:61], v[60:61], v[60:61] op_sel:[0,1] op_sel_hi:[1,0]
	global_load_dwordx4 v[2:5], v[2:3], off nt
	s_waitcnt vmcnt(1)
	v_mul_f32_e32 v70, v9, v9
	v_pk_fma_f32 v[70:71], v[8:9], v[8:9], v[70:71] op_sel_hi:[1,1,0]
	s_waitcnt vmcnt(0)
	v_mul_f32_e32 v51, v2, v2
	v_mul_f32_e32 v53, v3, v3
	v_mov_b32_e32 v37, v51
	v_mov_b32_e32 v61, v53
	v_pk_add_f32 v[36:37], v[36:37], v[60:61]
	v_mul_f32_e32 v60, v7, v7
	v_mul_f32_e32 v55, v4, v4
	v_mul_f32_e32 v57, v5, v5
	v_pk_fma_f32 v[60:61], v[6:7], v[6:7], v[60:61] op_sel_hi:[1,1,0]
	v_mov_b32_e32 v71, v57
	v_mov_b32_e32 v61, v55
	v_pk_add_f32 v[60:61], v[60:61], v[70:71]
	s_nop 0
	v_pk_add_f32 v[36:37], v[36:37], v[60:61]
	v_lshlrev_b64 v[60:61], 12, v[34:35]
	v_add_f32_e32 v36, v36, v37
	ds_bpermute_b32 v37, v62, v36
	s_waitcnt lgkmcnt(0)
	v_add_f32_e32 v36, v36, v37
	ds_bpermute_b32 v37, v63, v36
	s_waitcnt lgkmcnt(0)
	v_add_f32_e32 v36, v36, v37
	ds_bpermute_b32 v37, v64, v36
	s_waitcnt lgkmcnt(0)
	v_add_f32_e32 v36, v36, v37
	ds_bpermute_b32 v37, v65, v36
	s_waitcnt lgkmcnt(0)
	v_add_f32_e32 v36, v36, v37
	ds_bpermute_b32 v37, v66, v36
	s_waitcnt lgkmcnt(0)
	v_add_f32_e32 v36, v36, v37
	ds_bpermute_b32 v37, v67, v36
	s_waitcnt lgkmcnt(0)
	v_add_f32_e32 v36, v36, v37
	v_fmamk_f32 v36, v36, 0x3a000000, v199
	v_cmp_gt_f32_e32 vcc, s0, v36
	v_mul_f32_e32 v37, 0x4b800000, v36
	s_nop 0
	v_cndmask_b32_e32 v36, v36, v37, vcc
	v_rsq_f32_e32 v36, v36
	s_nop 0
	v_mul_f32_e32 v37, 0x45800000, v36
	v_cndmask_b32_e32 v51, v36, v37, vcc
	global_load_dwordx4 v[34:37], v[38:39], off
	v_mul_f32_e32 v30, v30, v51
	v_mul_f32_e32 v31, v31, v51
	v_mul_f32_e32 v32, v32, v51
	v_mul_f32_e32 v26, v26, v51
	v_mul_f32_e32 v27, v27, v51
	v_mul_f32_e32 v28, v28, v51
	v_mul_f32_e32 v29, v29, v51
	v_mul_f32_e32 v22, v22, v51
	v_mul_f32_e32 v23, v23, v51
	v_mul_f32_e32 v24, v24, v51
	v_mul_f32_e32 v25, v25, v51
	v_mul_f32_e32 v18, v18, v51
	v_mul_f32_e32 v19, v19, v51
	v_mul_f32_e32 v20, v20, v51
	v_mul_f32_e32 v21, v21, v51
	v_mul_f32_e32 v14, v14, v51
	v_mul_f32_e32 v15, v15, v51
	v_mul_f32_e32 v16, v16, v51
	v_mul_f32_e32 v17, v17, v51
	v_mul_f32_e32 v10, v10, v51
	v_mul_f32_e32 v11, v11, v51
	v_mul_f32_e32 v12, v12, v51
	v_mul_f32_e32 v13, v13, v51
	v_mul_f32_e32 v6, v6, v51
	v_mul_f32_e32 v7, v7, v51
	v_mul_f32_e32 v8, v8, v51
	v_mul_f32_e32 v9, v9, v51
	v_mul_f32_e32 v2, v2, v51
	v_mul_f32_e32 v3, v3, v51
	v_mul_f32_e32 v4, v4, v51
	v_mul_f32_e32 v5, v5, v51
	v_cmp_le_i32_e32 vcc, s30, v0
	s_or_b64 s[6:7], vcc, s[6:7]
	s_waitcnt vmcnt(0)
	v_mul_f32_e32 v30, v34, v30
	v_lshl_add_u32 v34, v69, 2, v68
	ds_read_b128 v[70:73], v34 offset:8192
	ds_read_b128 v[74:77], v34
	v_mul_f32_e32 v31, v35, v31
	v_mul_f32_e32 v32, v36, v32
	s_waitcnt lgkmcnt(1)
; __device__ __forceinline__ unsigned pk2(float lo, float hi) { unsigned r; asm volatile("v_cvt_pk_bf16_f32 %0, %1, %2" : "=v"(r) : "v"(lo), "v"(hi)); return r; }
; __device__ __forceinline__ void xn_phase(const Params& p, int layer, int which, char* smem) {
;     ...
;         for (int j = 0; j < 8; ++j) { const int c = 4 * (lane + 64 * j); const f32x4 gg = *(const f32x4*)(g + c); float y[4];
; #pragma unroll
;             for (int e = 0; e < 4; ++e) y[e] = v[j][e] * rinv * gg[e] * (1.f + sc[c + e]) + sh[c + e];
;             u32x2 o; o.x = pk2(y[0], y[1]); o.y = pk2(y[2], y[3]); *(u32x2*)(XN + (size_t)row * DM + c) = o; }
	v_add_f32_e32 v35, 1.0, v71
	s_waitcnt lgkmcnt(0)
	v_fma_f32 v31, v35, v31, v75
	v_add_f32_e32 v35, 1.0, v72
	v_add_f32_e32 v53, 1.0, v70
	v_fma_f32 v35, v35, v32, v76
	v_mul_f32_e32 v32, v33, v51
	v_fma_f32 v30, v53, v30, v74
	v_mul_f32_e32 v32, v37, v32
	v_add_f32_e32 v33, 1.0, v73
	v_fmac_f32_e32 v77, v33, v32
	v_cvt_pk_bf16_f32 v32, v30, v31
	v_lshl_add_u64 v[30:31], v[48:49], 0, v[60:61]
	v_cvt_pk_bf16_f32 v33, v35, v77
	global_store_dwordx2 v[30:31], v[32:33], off
	global_load_dwordx4 v[70:73], v[38:39], off offset:1024
	ds_read_b128 v[74:77], v34 offset:9216
	ds_read_b128 v[78:81], v34 offset:1024
	s_waitcnt lgkmcnt(1)
	v_add_f32_e32 v32, 1.0, v74
	s_waitcnt vmcnt(0)
	v_mul_f32_e32 v26, v26, v70
	s_waitcnt lgkmcnt(0)
	v_fma_f32 v26, v32, v26, v78
	v_mul_f32_e32 v27, v27, v71
	v_add_f32_e32 v32, 1.0, v75
	v_fma_f32 v27, v27, v32, v79
	v_mul_f32_e32 v28, v28, v72
	v_add_f32_e32 v32, 1.0, v76
	v_fma_f32 v28, v28, v32, v80
	v_mul_f32_e32 v29, v29, v73
	v_add_f32_e32 v32, 1.0, v77
	v_fmac_f32_e32 v81, v29, v32
	v_cvt_pk_bf16_f32 v26, v26, v27
	v_cvt_pk_bf16_f32 v27, v28, v81
	global_store_dwordx2 v[30:31], v[26:27], off offset:512
	global_load_dwordx4 v[26:29], v[38:39], off offset:2048
	ds_read_b128 v[70:73], v34 offset:10240
	ds_read_b128 v[74:77], v34 offset:2048
	s_waitcnt vmcnt(0)
	v_mul_f32_e32 v22, v22, v26
	s_waitcnt lgkmcnt(1)
	v_add_f32_e32 v26, 1.0, v70
	s_waitcnt lgkmcnt(0)
	v_fma_f32 v22, v26, v22, v74
	v_mul_f32_e32 v23, v23, v27
	v_add_f32_e32 v26, 1.0, v71
	v_fma_f32 v23, v23, v26, v75
	v_mul_f32_e32 v24, v24, v28
	v_add_f32_e32 v26, 1.0, v72
	v_fma_f32 v24, v24, v26, v76
	v_mul_f32_e32 v25, v25, v29
	v_add_f32_e32 v26, 1.0, v73
	v_fmac_f32_e32 v77, v25, v26
	v_cvt_pk_bf16_f32 v22, v22, v23
	v_cvt_pk_bf16_f32 v23, v24, v77
	global_store_dwordx2 v[30:31], v[22:23], off offset:1024
	global_load_dwordx4 v[22:25], v[38:39], off offset:3072
	ds_read_b128 v[26:29], v34 offset:11264
	ds_read_b128 v[70:73], v34 offset:3072
	s_waitcnt vmcnt(0)
	v_mul_f32_e32 v18, v18, v22
	s_waitcnt lgkmcnt(1)
	v_add_f32_e32 v22, 1.0, v26
	s_waitcnt lgkmcnt(0)
	v_fma_f32 v18, v22, v18, v70
	v_mul_f32_e32 v19, v19, v23
	v_add_f32_e32 v22, 1.0, v27
	v_fma_f32 v19, v19, v22, v71
	v_mul_f32_e32 v20, v20, v24
	v_add_f32_e32 v22, 1.0, v28
	v_fma_f32 v20, v20, v22, v72
	v_mul_f32_e32 v21, v21, v25
	v_add_f32_e32 v22, 1.0, v29
	v_fmac_f32_e32 v73, v21, v22
	v_cvt_pk_bf16_f32 v18, v18, v19
	v_cvt_pk_bf16_f32 v19, v20, v73
	global_store_dwordx2 v[30:31], v[18:19], off offset:1536
	global_load_dwordx4 v[18:21], v[40:41], off
	ds_read_b128 v[22:25], v34 offset:12288
	ds_read_b128 v[26:29], v34 offset:4096
	s_waitcnt vmcnt(0)
	v_mul_f32_e32 v14, v14, v18
	s_waitcnt lgkmcnt(1)
	v_add_f32_e32 v18, 1.0, v22
	s_waitcnt lgkmcnt(0)
	v_fma_f32 v14, v18, v14, v26
	v_mul_f32_e32 v15, v15, v19
	v_add_f32_e32 v18, 1.0, v23
	v_fma_f32 v15, v15, v18, v27
	v_mul_f32_e32 v16, v16, v20
	v_add_f32_e32 v18, 1.0, v24
	v_fma_f32 v16, v16, v18, v28
	v_mul_f32_e32 v17, v17, v21
	v_add_f32_e32 v18, 1.0, v25
	v_fmac_f32_e32 v29, v17, v18
	v_cvt_pk_bf16_f32 v14, v14, v15
	v_cvt_pk_bf16_f32 v15, v16, v29
	global_store_dwordx2 v[30:31], v[14:15], off offset:2048
	global_load_dwordx4 v[14:17], v[42:43], off
	ds_read_b128 v[18:21], v34 offset:13312
	ds_read_b128 v[22:25], v34 offset:5120
	s_waitcnt vmcnt(0)
	v_mul_f32_e32 v10, v10, v14
	s_waitcnt lgkmcnt(1)
	v_add_f32_e32 v14, 1.0, v18
	s_waitcnt lgkmcnt(0)
	v_fma_f32 v10, v14, v10, v22
	v_mul_f32_e32 v11, v11, v15
	v_add_f32_e32 v14, 1.0, v19
	v_fma_f32 v11, v11, v14, v23
	v_mul_f32_e32 v12, v12, v16
	v_add_f32_e32 v14, 1.0, v20
	v_fma_f32 v12, v12, v14, v24
	v_mul_f32_e32 v13, v13, v17
	v_add_f32_e32 v14, 1.0, v21
	v_fmac_f32_e32 v25, v13, v14
	v_cvt_pk_bf16_f32 v10, v10, v11
	v_cvt_pk_bf16_f32 v11, v12, v25
	global_store_dwordx2 v[30:31], v[10:11], off offset:2560
	global_load_dwordx4 v[10:13], v[44:45], off
	ds_read_b128 v[14:17], v34 offset:14336
	ds_read_b128 v[18:21], v34 offset:6144
	s_waitcnt vmcnt(0)
	v_mul_f32_e32 v6, v6, v10
	s_waitcnt lgkmcnt(1)
	v_add_f32_e32 v10, 1.0, v14
	s_waitcnt lgkmcnt(0)
	v_fma_f32 v6, v10, v6, v18
	v_mul_f32_e32 v7, v7, v11
	v_add_f32_e32 v10, 1.0, v15
	v_fma_f32 v7, v7, v10, v19
	v_mul_f32_e32 v8, v8, v12
	v_add_f32_e32 v10, 1.0, v16
	v_fma_f32 v8, v8, v10, v20
	v_mul_f32_e32 v9, v9, v13
	v_add_f32_e32 v10, 1.0, v17
	v_fmac_f32_e32 v21, v9, v10
	v_cvt_pk_bf16_f32 v6, v6, v7
	v_cvt_pk_bf16_f32 v7, v8, v21
	global_store_dwordx2 v[30:31], v[6:7], off offset:3072
	global_load_dwordx4 v[6:9], v[46:47], off
	ds_read_b128 v[10:13], v34 offset:15360
	ds_read_b128 v[14:17], v34 offset:7168
	s_waitcnt vmcnt(0)
	v_mul_f32_e32 v2, v2, v6
	s_waitcnt lgkmcnt(1)
	v_add_f32_e32 v6, 1.0, v10
	s_waitcnt lgkmcnt(0)
	v_fma_f32 v2, v6, v2, v14
	v_mul_f32_e32 v3, v3, v7
	v_add_f32_e32 v6, 1.0, v11
	v_fma_f32 v3, v3, v6, v15
	v_mul_f32_e32 v4, v4, v8
	v_add_f32_e32 v6, 1.0, v12
	v_fma_f32 v4, v4, v6, v16
	v_mul_f32_e32 v5, v5, v9
	v_add_f32_e32 v6, 1.0, v13
	v_fmac_f32_e32 v17, v5, v6
	v_cvt_pk_bf16_f32 v2, v2, v3
	v_cvt_pk_bf16_f32 v3, v4, v17
	global_store_dwordx2 v[30:31], v[2:3], off offset:3584
	s_andn2_b64 exec, exec, s[6:7]
	s_cbranch_execz .LBB0_1339

; __device__ __forceinline__ int ltid() { int t = threadIdx.x; asm volatile("" : "+v"(t)); return t; }
; __device__ __forceinline__ void final_norm(const Params& p) {
;     const int wid = ltid() >> 6, lane = ltid() & 63; const float* g = p.in[32];
;     for (int row = blockIdx.x * 8 + wid; row < SEQ; row += gridDim.x * 8) { float* src = p.out + (size_t)row * DM; f32x4 v[8]; float ss = 0.f;
; #pragma unroll
;         for (int j = 0; j < 8; ++j) { v[j] = *(const f32x4*)(src + 4 * (lane + 64 * j)); ss += (v[j][0] * v[j][0] + v[j][1] * v[j][1]) + (v[j][2] * v[j][2] + v[j][3] * v[j][3]); }
;         const float rinv = rsqrtf(wave_sum(ss) * (1.f / DM) + 1e-6f);
; #pragma unroll
;         for (int j = 0; j < 8; ++j) { const int c = 4 * (lane + 64 * j); const f32x4 gg = *(const f32x4*)(g + c); *(f32x4*)(src + c) = v[j] * rinv * gg; }
;     }
.LBB0_1676:
	v_ashrrev_i32_e32 v1, 31, v0
	v_lshlrev_b64 v[30:31], 13, v[0:1]
	v_lshl_add_u64 v[58:59], s[6:7], 0, v[30:31]
	v_lshl_add_u64 v[66:67], v[58:59], 0, v[2:3]
	global_load_dwordx4 v[30:33], v[66:67], off nt
	global_load_dwordx4 v[34:37], v[66:67], off offset:1024 nt
	global_load_dwordx4 v[38:41], v[66:67], off offset:2048 nt
	v_lshl_add_u64 v[68:69], v[58:59], 0, v[14:15]
	global_load_dwordx4 v[42:45], v[68:69], off nt
	global_load_dwordx4 v[46:49], v[66:67], off offset:3072 nt
	v_lshl_add_u64 v[70:71], v[58:59], 0, v[16:17]
	global_load_dwordx4 v[50:53], v[70:71], off nt
	v_lshl_add_u64 v[72:73], v[58:59], 0, v[20:21]
	v_lshl_add_u64 v[74:75], v[58:59], 0, v[18:19]
	global_load_dwordx4 v[54:57], v[72:73], off nt
	global_load_dwordx4 v[58:61], v[74:75], off nt
	global_load_dwordx4 v[62:65], v[4:5], off
	v_add_u32_e32 v0, s95, v0
	s_waitcnt vmcnt(0)
	v_mov_b32_e32 v78, v31
	v_mov_b32_e32 v79, v35
	v_mov_b32_e32 v82, v33
	v_mov_b32_e32 v83, v37
	v_mov_b32_e32 v76, v30
	v_mov_b32_e32 v77, v34
	v_mov_b32_e32 v80, v32
	v_mov_b32_e32 v81, v36
	v_pk_mul_f32 v[84:85], v[40:41], v[40:41]
	v_pk_mul_f32 v[86:87], v[38:39], v[38:39]
	v_pk_mul_f32 v[78:79], v[78:79], v[78:79]
	v_pk_mul_f32 v[82:83], v[82:83], v[82:83]
	v_pk_mov_b32 v[100:101], v[86:87], v[84:85] op_sel:[1,0]
	v_mov_b32_e32 v87, v85
	v_pk_fma_f32 v[76:77], v[76:77], v[76:77], v[78:79]
	v_pk_fma_f32 v[78:79], v[80:81], v[80:81], v[82:83]
	v_mul_f32_e32 v88, v47, v47
	v_mul_f32_e32 v90, v49, v49
	v_pk_add_f32 v[80:81], v[100:101], v[86:87]
	v_pk_add_f32 v[76:77], v[76:77], v[78:79]
	v_mul_f32_e32 v1, v42, v42
	v_mul_f32_e32 v29, v43, v43
	v_mul_f32_e32 v99, v44, v44
	v_mul_f32_e32 v102, v45, v45
	v_pk_fma_f32 v[84:85], v[46:47], v[46:47], v[88:89] op_sel_hi:[1,1,0]
	v_pk_fma_f32 v[88:89], v[48:49], v[48:49], v[90:91] op_sel_hi:[1,1,0]
	v_pk_add_f32 v[78:79], v[80:81], v[80:81] op_sel:[0,1] op_sel_hi:[1,0]
	v_pk_add_f32 v[76:77], v[76:77], v[76:77] op_sel:[0,1] op_sel_hi:[1,0]
	v_pk_mul_f32 v[92:93], v[52:53], v[52:53]
	v_pk_mul_f32 v[94:95], v[50:51], v[50:51]
	v_mov_b32_e32 v85, v99
	v_mov_b32_e32 v89, v102
	v_mov_b32_e32 v79, v29
	v_mov_b32_e32 v77, v1
	v_pk_mov_b32 v[90:91], v[94:95], v[92:93] op_sel:[1,0]
	v_mov_b32_e32 v95, v93
	v_pk_add_f32 v[80:81], v[84:85], v[88:89]
	v_pk_add_f32 v[76:77], v[76:77], v[78:79]
	v_mul_f32_e32 v96, v59, v59
	v_mul_f32_e32 v98, v61, v61
	v_pk_add_f32 v[82:83], v[90:91], v[94:95]
	v_pk_add_f32 v[76:77], v[76:77], v[80:81]
	v_mul_f32_e32 v103, v54, v54
	v_mul_f32_e32 v104, v55, v55
	v_mul_f32_e32 v105, v56, v56
	v_mul_f32_e32 v106, v57, v57
	v_pk_fma_f32 v[92:93], v[58:59], v[58:59], v[96:97] op_sel_hi:[1,1,0]
	v_pk_fma_f32 v[96:97], v[60:61], v[60:61], v[98:99] op_sel_hi:[1,1,0]
	v_pk_add_f32 v[82:83], v[82:83], v[82:83] op_sel:[0,1] op_sel_hi:[1,0]
	v_pk_add_f32 v[76:77], v[76:77], v[76:77] op_sel:[0,1] op_sel_hi:[1,0]
	v_mov_b32_e32 v93, v105
	v_mov_b32_e32 v97, v106
	v_mov_b32_e32 v83, v104
	v_mov_b32_e32 v77, v103
	v_pk_add_f32 v[84:85], v[92:93], v[96:97]
	v_pk_add_f32 v[76:77], v[76:77], v[82:83]
	s_nop 0
	v_pk_add_f32 v[76:77], v[76:77], v[84:85]
	s_nop 0
	v_add_f32_e32 v1, v76, v77
	ds_bpermute_b32 v29, v22, v1
	s_waitcnt lgkmcnt(0)
	v_add_f32_e32 v1, v1, v29
	ds_bpermute_b32 v29, v23, v1
	s_waitcnt lgkmcnt(0)
	v_add_f32_e32 v1, v1, v29
	ds_bpermute_b32 v29, v24, v1
	s_waitcnt lgkmcnt(0)
	v_add_f32_e32 v1, v1, v29
	ds_bpermute_b32 v29, v25, v1
	s_waitcnt lgkmcnt(0)
	v_add_f32_e32 v1, v1, v29
	ds_bpermute_b32 v29, v26, v1
	s_waitcnt lgkmcnt(0)
	v_add_f32_e32 v1, v1, v29
	ds_bpermute_b32 v29, v27, v1
	s_waitcnt lgkmcnt(0)
	v_add_f32_e32 v1, v1, v29
	v_fmamk_f32 v1, v1, 0x3a000000, v28
	v_mul_f32_e32 v29, 0x4b800000, v1
	v_cmp_gt_f32_e32 vcc, s4, v1
	s_nop 1
	v_cndmask_b32_e32 v1, v1, v29, vcc
	v_rsq_f32_e32 v1, v1
	s_nop 0
	v_mul_f32_e32 v29, 0x45800000, v1
	v_cndmask_b32_e32 v76, v1, v29, vcc
	v_pk_mul_f32 v[30:31], v[30:31], v[76:77] op_sel_hi:[1,0]
	v_pk_mul_f32 v[32:33], v[32:33], v[76:77] op_sel_hi:[1,0]
	v_pk_mul_f32 v[30:31], v[62:63], v[30:31]
	v_pk_mul_f32 v[32:33], v[64:65], v[32:33]
	global_store_dwordx4 v[66:67], v[30:33], off
	global_load_dwordx4 v[30:33], v[4:5], off offset:1024
	v_pk_mul_f32 v[36:37], v[36:37], v[76:77] op_sel_hi:[1,0]
	v_pk_mul_f32 v[34:35], v[34:35], v[76:77] op_sel_hi:[1,0]
	v_cmp_lt_i32_e32 vcc, s5, v0
	s_or_b64 s[2:3], vcc, s[2:3]
	s_waitcnt vmcnt(0)
	v_pk_mul_f32 v[30:31], v[30:31], v[34:35]
	v_pk_mul_f32 v[32:33], v[32:33], v[36:37]
	global_store_dwordx4 v[66:67], v[30:33], off offset:1024
	global_load_dwordx4 v[30:33], v[4:5], off offset:2048
	v_pk_mul_f32 v[34:35], v[40:41], v[76:77] op_sel_hi:[1,0]
	v_pk_mul_f32 v[36:37], v[38:39], v[76:77] op_sel_hi:[1,0]
	s_waitcnt vmcnt(0)
	v_pk_mul_f32 v[32:33], v[32:33], v[34:35]
	v_pk_mul_f32 v[30:31], v[30:31], v[36:37]
	global_store_dwordx4 v[66:67], v[30:33], off offset:2048
	global_load_dwordx4 v[30:33], v[4:5], off offset:3072
	v_pk_mul_f32 v[34:35], v[48:49], v[76:77] op_sel_hi:[1,0]
	v_pk_mul_f32 v[36:37], v[46:47], v[76:77] op_sel_hi:[1,0]
	s_waitcnt vmcnt(0)
	v_pk_mul_f32 v[32:33], v[32:33], v[34:35]
	v_pk_mul_f32 v[30:31], v[30:31], v[36:37]
	global_store_dwordx4 v[66:67], v[30:33], off offset:3072
	global_load_dwordx4 v[30:33], v[6:7], off
	v_pk_mul_f32 v[34:35], v[44:45], v[76:77] op_sel_hi:[1,0]
	v_pk_mul_f32 v[36:37], v[42:43], v[76:77] op_sel_hi:[1,0]
	s_waitcnt vmcnt(0)
	v_pk_mul_f32 v[32:33], v[32:33], v[34:35]
	v_pk_mul_f32 v[30:31], v[30:31], v[36:37]
	global_store_dwordx4 v[68:69], v[30:33], off
	global_load_dwordx4 v[30:33], v[8:9], off
	v_pk_mul_f32 v[34:35], v[52:53], v[76:77] op_sel_hi:[1,0]
	v_pk_mul_f32 v[36:37], v[50:51], v[76:77] op_sel_hi:[1,0]
	s_waitcnt vmcnt(0)
	v_pk_mul_f32 v[32:33], v[32:33], v[34:35]
	v_pk_mul_f32 v[30:31], v[30:31], v[36:37]
	global_store_dwordx4 v[70:71], v[30:33], off
	global_load_dwordx4 v[30:33], v[10:11], off
	v_pk_mul_f32 v[34:35], v[60:61], v[76:77] op_sel_hi:[1,0]
	v_pk_mul_f32 v[36:37], v[58:59], v[76:77] op_sel_hi:[1,0]
	s_waitcnt vmcnt(0)
	v_pk_mul_f32 v[32:33], v[32:33], v[34:35]
	v_pk_mul_f32 v[30:31], v[30:31], v[36:37]
	global_store_dwordx4 v[74:75], v[30:33], off
	global_load_dwordx4 v[30:33], v[12:13], off
	v_pk_mul_f32 v[34:35], v[56:57], v[76:77] op_sel_hi:[1,0]
	v_pk_mul_f32 v[36:37], v[54:55], v[76:77] op_sel_hi:[1,0]
	s_waitcnt vmcnt(0)
	v_pk_mul_f32 v[32:33], v[34:35], v[32:33]
	v_pk_mul_f32 v[30:31], v[36:37], v[30:31]
	global_store_dwordx4 v[72:73], v[30:33], off
	s_andn2_b64 exec, exec, s[2:3]
	s_cbranch_execnz .LBB0_1676
